# small_res_unit K loops software-pipelined (batched operand loads, counted vmcnt)
# speedup vs baseline: 1.0056x; 1.0036x over previous
.LBB0_539:
	v_lshl_add_u64 v[18:19], v[14:15], 0, s[0:1]
	v_lshl_add_u64 v[16:17], v[12:13], 0, s[0:1]
	v_add_co_u32_e32 v16, vcc, 0x14c58000, v16
	s_add_u32 s0, s0, 0x600
	s_nop 1
	v_addc_co_u32_e32 v17, vcc, 0, v17, vcc
	s_addc_u32 s1, s1, 0
	s_cmpk_lg_i32 s0, 0xc00
	global_load_dwordx4 v[36:39], v[18:19], off offset:-768
	global_load_dwordx4 v[84:87], v[16:17], off offset:1024
	global_load_dwordx4 v[40:43], v[18:19], off offset:-704
	global_load_dwordx4 v[88:91], v[16:17], off offset:1088
	global_load_dwordx4 v[44:47], v[18:19], off offset:-640
	global_load_dwordx4 v[92:95], v[16:17], off offset:1152
	global_load_dwordx4 v[48:51], v[18:19], off offset:-576
	global_load_dwordx4 v[96:99], v[16:17], off offset:1216
	global_load_dwordx4 v[52:55], v[18:19], off offset:-512
	global_load_dwordx4 v[100:103], v[16:17], off offset:1280
	global_load_dwordx4 v[56:59], v[18:19], off offset:-448
	global_load_dwordx4 v[104:107], v[16:17], off offset:1344
	global_load_dwordx4 v[60:63], v[18:19], off offset:-384
	global_load_dwordx4 v[108:111], v[16:17], off offset:1408
	global_load_dwordx4 v[64:67], v[18:19], off offset:-320
	global_load_dwordx4 v[112:115], v[16:17], off offset:1472
	global_load_dwordx4 v[68:71], v[18:19], off offset:-256
	global_load_dwordx4 v[116:119], v[16:17], off offset:1536
	global_load_dwordx4 v[72:75], v[18:19], off offset:-192
	global_load_dwordx4 v[120:123], v[16:17], off offset:1600
	global_load_dwordx4 v[76:79], v[18:19], off offset:-128
	global_load_dwordx4 v[124:127], v[16:17], off offset:1664
	global_load_dwordx4 v[80:83], v[18:19], off offset:-64
	global_load_dwordx4 v[128:131], v[16:17], off offset:1728
	s_waitcnt vmcnt(22)
	v_mfma_f32_16x16x32_bf16 v[4:7], v[36:39], v[84:87], v[4:7]
	global_load_dwordx4 v[36:39], v[18:19], off
	global_load_dwordx4 v[84:87], v[16:17], off offset:1792
	s_waitcnt vmcnt(22)
	v_mfma_f32_16x16x32_bf16 v[4:7], v[40:43], v[88:91], v[4:7]
	global_load_dwordx4 v[40:43], v[18:19], off offset:64
	global_load_dwordx4 v[88:91], v[16:17], off offset:1856
	s_waitcnt vmcnt(22)
	v_mfma_f32_16x16x32_bf16 v[4:7], v[44:47], v[92:95], v[4:7]
	global_load_dwordx4 v[44:47], v[18:19], off offset:128
	global_load_dwordx4 v[92:95], v[16:17], off offset:1920
	s_waitcnt vmcnt(22)
	v_mfma_f32_16x16x32_bf16 v[4:7], v[48:51], v[96:99], v[4:7]
	global_load_dwordx4 v[48:51], v[18:19], off offset:192
	global_load_dwordx4 v[96:99], v[16:17], off offset:1984
	s_waitcnt vmcnt(22)
	v_mfma_f32_16x16x32_bf16 v[4:7], v[52:55], v[100:103], v[4:7]
	global_load_dwordx4 v[52:55], v[18:19], off offset:256
	global_load_dwordx4 v[100:103], v[16:17], off offset:2048
	s_waitcnt vmcnt(22)
	v_mfma_f32_16x16x32_bf16 v[4:7], v[56:59], v[104:107], v[4:7]
	global_load_dwordx4 v[56:59], v[18:19], off offset:320
	global_load_dwordx4 v[104:107], v[16:17], off offset:2112
	s_waitcnt vmcnt(22)
	v_mfma_f32_16x16x32_bf16 v[4:7], v[60:63], v[108:111], v[4:7]
	global_load_dwordx4 v[60:63], v[18:19], off offset:384
	global_load_dwordx4 v[108:111], v[16:17], off offset:2176
	s_waitcnt vmcnt(22)
	v_mfma_f32_16x16x32_bf16 v[4:7], v[64:67], v[112:115], v[4:7]
	global_load_dwordx4 v[64:67], v[18:19], off offset:448
	global_load_dwordx4 v[112:115], v[16:17], off offset:2240
	s_waitcnt vmcnt(22)
	v_mfma_f32_16x16x32_bf16 v[4:7], v[68:71], v[116:119], v[4:7]
	global_load_dwordx4 v[68:71], v[18:19], off offset:512
	global_load_dwordx4 v[116:119], v[16:17], off offset:2304
	s_waitcnt vmcnt(22)
	v_mfma_f32_16x16x32_bf16 v[4:7], v[72:75], v[120:123], v[4:7]
	global_load_dwordx4 v[72:75], v[18:19], off offset:576
	global_load_dwordx4 v[120:123], v[16:17], off offset:2368
	s_waitcnt vmcnt(22)
	v_mfma_f32_16x16x32_bf16 v[4:7], v[76:79], v[124:127], v[4:7]
	global_load_dwordx4 v[76:79], v[18:19], off offset:640
	global_load_dwordx4 v[124:127], v[16:17], off offset:2432
	s_waitcnt vmcnt(22)
	v_mfma_f32_16x16x32_bf16 v[4:7], v[80:83], v[128:131], v[4:7]
	global_load_dwordx4 v[80:83], v[18:19], off offset:704
	global_load_dwordx4 v[128:131], v[16:17], off offset:2496
	s_waitcnt vmcnt(22)
	v_mfma_f32_16x16x32_bf16 v[4:7], v[36:39], v[84:87], v[4:7]
	s_waitcnt vmcnt(20)
	v_mfma_f32_16x16x32_bf16 v[4:7], v[40:43], v[88:91], v[4:7]
	s_waitcnt vmcnt(18)
	v_mfma_f32_16x16x32_bf16 v[4:7], v[44:47], v[92:95], v[4:7]
	s_waitcnt vmcnt(16)
	v_mfma_f32_16x16x32_bf16 v[4:7], v[48:51], v[96:99], v[4:7]
	s_waitcnt vmcnt(14)
	v_mfma_f32_16x16x32_bf16 v[4:7], v[52:55], v[100:103], v[4:7]
	s_waitcnt vmcnt(12)
	v_mfma_f32_16x16x32_bf16 v[4:7], v[56:59], v[104:107], v[4:7]
	s_waitcnt vmcnt(10)
	v_mfma_f32_16x16x32_bf16 v[4:7], v[60:63], v[108:111], v[4:7]
	s_waitcnt vmcnt(8)
	v_mfma_f32_16x16x32_bf16 v[4:7], v[64:67], v[112:115], v[4:7]
	s_waitcnt vmcnt(6)
	v_mfma_f32_16x16x32_bf16 v[4:7], v[68:71], v[116:119], v[4:7]
	s_waitcnt vmcnt(4)
	v_mfma_f32_16x16x32_bf16 v[4:7], v[72:75], v[120:123], v[4:7]
	s_waitcnt vmcnt(2)
	v_mfma_f32_16x16x32_bf16 v[4:7], v[76:79], v[124:127], v[4:7]
	s_waitcnt vmcnt(0)
	v_mfma_f32_16x16x32_bf16 v[4:7], v[80:83], v[128:131], v[4:7]
	s_cbranch_scc1 .LBB0_539
	s_lshl_b32 s0, s5, 1
	s_and_b32 s10, s0, 0xffffffe0
	s_add_i32 s10, s10, 0x8000
	v_add_u32_e32 v12, s10, v20
	v_ashrrev_i32_e32 v13, 31, v12
	v_readlane_b32 s0, v255, 9
	v_lshlrev_b64 v[12:13], 11, v[12:13]
	v_readlane_b32 s1, v255, 10
	s_lshl_b32 s8, s7, 1
	v_mov_b32_e32 v11, v3
	v_lshl_add_u64 v[12:13], s[0:1], 0, v[12:13]
	v_lshl_add_u64 v[12:13], v[12:13], 0, s[8:9]
	v_lshl_add_u64 v[12:13], v[12:13], 0, v[10:11]
	global_load_dwordx2 v[14:15], v[12:13], off
	s_waitcnt vmcnt(0)
	v_lshlrev_b32_e32 v16, 16, v14
	v_and_b32_e32 v17, 0xffff0000, v14
	v_lshlrev_b32_e32 v14, 16, v15
	v_and_b32_e32 v15, 0xffff0000, v15
	v_pk_add_f32 v[6:7], v[6:7], v[14:15]
	v_pk_add_f32 v[14:15], v[4:5], v[16:17]
	v_mul_f32_e32 v4, v7, v7
	v_mul_f32_e32 v2, v15, v15
	v_fmac_f32_e32 v2, v14, v14
	v_fmac_f32_e32 v4, v6, v6
	v_add_f32_e32 v2, v2, v4
	ds_bpermute_b32 v4, v21, v2
	v_cvt_pk_bf16_f32 v14, v14, v15
	v_cvt_pk_bf16_f32 v15, v6, v7
	global_store_dwordx2 v[12:13], v[14:15], off
	s_waitcnt lgkmcnt(0)
	v_add_f32_e32 v2, v2, v4
	ds_bpermute_b32 v4, v22, v2
	s_and_saveexec_b64 s[0:1], s[38:39]
	s_cbranch_execz .LBB0_542
	s_waitcnt lgkmcnt(0)
	v_add_f32_e32 v2, v2, v4
	ds_write_b32 v24, v2

.LBB0_902:
	v_lshl_add_u64 v[18:19], v[14:15], 0, s[2:3]
	v_lshl_add_u64 v[16:17], v[12:13], 0, s[2:3]
	v_add_co_u32_e32 v16, vcc, 0x7918000, v16
	s_add_u32 s2, s2, 0x580
	s_nop 1
	v_addc_co_u32_e32 v17, vcc, 0, v17, vcc
	s_addc_u32 s3, s3, 0
	s_cmpk_lg_i32 s2, 0x1600
	global_load_dwordx4 v[36:39], v[18:19], off offset:-704
	global_load_dwordx4 v[84:87], v[16:17], off offset:1024
	global_load_dwordx4 v[40:43], v[18:19], off offset:-640
	global_load_dwordx4 v[88:91], v[16:17], off offset:1088
	global_load_dwordx4 v[44:47], v[18:19], off offset:-576
	global_load_dwordx4 v[92:95], v[16:17], off offset:1152
	global_load_dwordx4 v[48:51], v[18:19], off offset:-512
	global_load_dwordx4 v[96:99], v[16:17], off offset:1216
	global_load_dwordx4 v[52:55], v[18:19], off offset:-448
	global_load_dwordx4 v[100:103], v[16:17], off offset:1280
	global_load_dwordx4 v[56:59], v[18:19], off offset:-384
	global_load_dwordx4 v[104:107], v[16:17], off offset:1344
	global_load_dwordx4 v[60:63], v[18:19], off offset:-320
	global_load_dwordx4 v[108:111], v[16:17], off offset:1408
	global_load_dwordx4 v[64:67], v[18:19], off offset:-256
	global_load_dwordx4 v[112:115], v[16:17], off offset:1472
	global_load_dwordx4 v[68:71], v[18:19], off offset:-192
	global_load_dwordx4 v[116:119], v[16:17], off offset:1536
	global_load_dwordx4 v[72:75], v[18:19], off offset:-128
	global_load_dwordx4 v[120:123], v[16:17], off offset:1600
	global_load_dwordx4 v[76:79], v[18:19], off offset:-64
	global_load_dwordx4 v[124:127], v[16:17], off offset:1664
	s_waitcnt vmcnt(20)
	v_mfma_f32_16x16x32_bf16 v[4:7], v[36:39], v[84:87], v[4:7]
	global_load_dwordx4 v[36:39], v[18:19], off
	global_load_dwordx4 v[84:87], v[16:17], off offset:1728
	s_waitcnt vmcnt(20)
	v_mfma_f32_16x16x32_bf16 v[4:7], v[40:43], v[88:91], v[4:7]
	global_load_dwordx4 v[40:43], v[18:19], off offset:64
	global_load_dwordx4 v[88:91], v[16:17], off offset:1792
	s_waitcnt vmcnt(20)
	v_mfma_f32_16x16x32_bf16 v[4:7], v[44:47], v[92:95], v[4:7]
	global_load_dwordx4 v[44:47], v[18:19], off offset:128
	global_load_dwordx4 v[92:95], v[16:17], off offset:1856
	s_waitcnt vmcnt(20)
	v_mfma_f32_16x16x32_bf16 v[4:7], v[48:51], v[96:99], v[4:7]
	global_load_dwordx4 v[48:51], v[18:19], off offset:192
	global_load_dwordx4 v[96:99], v[16:17], off offset:1920
	s_waitcnt vmcnt(20)
	v_mfma_f32_16x16x32_bf16 v[4:7], v[52:55], v[100:103], v[4:7]
	global_load_dwordx4 v[52:55], v[18:19], off offset:256
	global_load_dwordx4 v[100:103], v[16:17], off offset:1984
	s_waitcnt vmcnt(20)
	v_mfma_f32_16x16x32_bf16 v[4:7], v[56:59], v[104:107], v[4:7]
	global_load_dwordx4 v[56:59], v[18:19], off offset:320
	global_load_dwordx4 v[104:107], v[16:17], off offset:2048
	s_waitcnt vmcnt(20)
	v_mfma_f32_16x16x32_bf16 v[4:7], v[60:63], v[108:111], v[4:7]
	global_load_dwordx4 v[60:63], v[18:19], off offset:384
	global_load_dwordx4 v[108:111], v[16:17], off offset:2112
	s_waitcnt vmcnt(20)
	v_mfma_f32_16x16x32_bf16 v[4:7], v[64:67], v[112:115], v[4:7]
	global_load_dwordx4 v[64:67], v[18:19], off offset:448
	global_load_dwordx4 v[112:115], v[16:17], off offset:2176
	s_waitcnt vmcnt(20)
	v_mfma_f32_16x16x32_bf16 v[4:7], v[68:71], v[116:119], v[4:7]
	global_load_dwordx4 v[68:71], v[18:19], off offset:512
	global_load_dwordx4 v[116:119], v[16:17], off offset:2240
	s_waitcnt vmcnt(20)
	v_mfma_f32_16x16x32_bf16 v[4:7], v[72:75], v[120:123], v[4:7]
	global_load_dwordx4 v[72:75], v[18:19], off offset:576
	global_load_dwordx4 v[120:123], v[16:17], off offset:2304
	s_waitcnt vmcnt(20)
	v_mfma_f32_16x16x32_bf16 v[4:7], v[76:79], v[124:127], v[4:7]
	global_load_dwordx4 v[76:79], v[18:19], off offset:640
	global_load_dwordx4 v[124:127], v[16:17], off offset:2368
	s_waitcnt vmcnt(20)
	v_mfma_f32_16x16x32_bf16 v[4:7], v[36:39], v[84:87], v[4:7]
	s_waitcnt vmcnt(18)
	v_mfma_f32_16x16x32_bf16 v[4:7], v[40:43], v[88:91], v[4:7]
	s_waitcnt vmcnt(16)
	v_mfma_f32_16x16x32_bf16 v[4:7], v[44:47], v[92:95], v[4:7]
	s_waitcnt vmcnt(14)
	v_mfma_f32_16x16x32_bf16 v[4:7], v[48:51], v[96:99], v[4:7]
	s_waitcnt vmcnt(12)
	v_mfma_f32_16x16x32_bf16 v[4:7], v[52:55], v[100:103], v[4:7]
	s_waitcnt vmcnt(10)
	v_mfma_f32_16x16x32_bf16 v[4:7], v[56:59], v[104:107], v[4:7]
	s_waitcnt vmcnt(8)
	v_mfma_f32_16x16x32_bf16 v[4:7], v[60:63], v[108:111], v[4:7]
	s_waitcnt vmcnt(6)
	v_mfma_f32_16x16x32_bf16 v[4:7], v[64:67], v[112:115], v[4:7]
	s_waitcnt vmcnt(4)
	v_mfma_f32_16x16x32_bf16 v[4:7], v[68:71], v[116:119], v[4:7]
	s_waitcnt vmcnt(2)
	v_mfma_f32_16x16x32_bf16 v[4:7], v[72:75], v[120:123], v[4:7]
	s_waitcnt vmcnt(0)
	v_mfma_f32_16x16x32_bf16 v[4:7], v[76:79], v[124:127], v[4:7]
	s_cbranch_scc1 .LBB0_902
	s_lshl_b32 s2, s7, 1
	s_and_b32 s11, s2, 0xffffffe0
	s_add_i32 s11, s11, 0x8000
	v_add_u32_e32 v12, s11, v1
	v_ashrrev_i32_e32 v13, 31, v12
	v_lshlrev_b64 v[12:13], 10, v[12:13]
	v_or_b32_e32 v2, s10, v12
	v_or_b32_e32 v12, v2, v0
	v_lshl_add_u64 v[14:15], v[12:13], 1, s[20:21]
	global_load_dwordx2 v[16:17], v[14:15], off
	s_andn2_b64 vcc, exec, s[0:1]
	s_waitcnt vmcnt(0)
	v_lshlrev_b32_e32 v18, 16, v16
	v_and_b32_e32 v19, 0xffff0000, v16
	v_lshlrev_b32_e32 v16, 16, v17
	v_and_b32_e32 v17, 0xffff0000, v17
	v_pk_add_f32 v[6:7], v[6:7], v[16:17]
	v_pk_add_f32 v[4:5], v[4:5], v[18:19]
	s_cbranch_vccnz .LBB0_905
	v_lshl_add_u64 v[12:13], v[12:13], 2, s[78:79]
	global_store_dwordx4 v[12:13], v[4:7], off
